# v49: v42 stack (P6 XCD swap, FoX rc fix + loop rotation, barrier follower shortcut, w_down transposes in P2 tail) + relaxed end-of-GEMM drains in P4/P6/P7
# speedup vs baseline: 1.0025x; 1.0007x over previous
;     DI void fused(pg8::f32x4 (&acc)[2][2][4][2], const pg8::Unit& u, int wr, int wc, int fr, int fq, pg8::PG8_LAS_T ldsp, int wid, int lane) const {
;         float* P = (float*)(unsigned char*)ldsp;
;         float* ST = P + 2048;
;         const int tid = wid * 64 + lane;
;         f32x4 gi[2][2], bi[2][2];
; #pragma unroll
;         for (int bj = 0; bj < 2; ++bj) {
;             const int col = u.pn * 256 + bj * 128 + wc * 32 + 8 * fq;
;             if (MODE == 0) { gi[bj][0] = *(const f32x4*)(g_in + col); gi[bj][1] = *(const f32x4*)(g_in + col + 4); bi[bj][0] = *(const f32x4*)(b_in + col); bi[bj][1] = *(const f32x4*)(b_in + col + 4); }
;         }
; #pragma unroll
;         for (int ai = 0; ai < 2; ++ai)
; #pragma unroll
;             for (int m = 0; m < 4; ++m) {
;                 const int rt = ai * 128 + wr * 64 + m * 16 + fr, row = u.pm * 256 + rt;
;                 float sm = 0.f, sq = 0.f;
;                 float mu = 0.f, rs = 0.f;
;                 if (MODE == 0) { mu = stats[row * 2]; rs = stats[row * 2 + 1]; }
; #pragma unroll
;                 for (int bj = 0; bj < 2; ++bj) {
;                     const int col = u.pn * 256 + bj * 128 + wc * 32 + 8 * fq;
;                     const size_t idx = (size_t)row * DM + col;
;                     f32x4 v0, v1;
;                     if (MODE == 0) {
;                         const f32x4 x0 = *(const f32x4*)(x + idx), x1 = *(const f32x4*)(x + idx + 4);
;                         v0 = ((x0 - mu) * rs * gi[bj][0] + bi[bj][0]) * ALPHA + acc[ai][bj][m][0];
;                         v1 = ((x1 - mu) * rs * gi[bj][1] + bi[bj][1]) * ALPHA + acc[ai][bj][m][1];
;                     } else {
;                         const u32x4 w = *(const u32x4*)(pg + idx);
;                         const u32x4 hw = *(const u32x4*)(h1 + idx);
;                         v0 = (f32x4){bflo(hw.x), bfhi(hw.x), bflo(hw.y), bfhi(hw.y)} * ALPHA + acc[ai][bj][m][0];
;                         v1 = (f32x4){bflo(hw.z), bfhi(hw.z), bflo(hw.w), bfhi(hw.w)} * ALPHA + acc[ai][bj][m][1];
;                         v0[0] += bflo(w.x); v0[1] += bfhi(w.x); v0[2] += bflo(w.y); v0[3] += bfhi(w.y);
;                         v1[0] += bflo(w.z); v1[1] += bfhi(w.z); v1[2] += bflo(w.w); v1[3] += bfhi(w.w);
;                     }
;                     acc[ai][bj][m][0] = v0; acc[ai][bj][m][1] = v1;
; #pragma unroll
.LBB0_722:
	s_add_u32 s0, s80, 0x1c80000
	v_lshrrev_b32_e32 v128, 1, v162
	s_addc_u32 s1, s81, 0
	v_and_b32_e32 v128, 24, v128
	s_lshl_b32 s5, s4, 8
	v_lshl_or_b32 v128, s6, 8, v128
	v_readlane_b32 s2, v255, 35
	v_add_u32_e32 v164, s5, v196
	v_ashrrev_i32_e32 v165, 31, v164
	v_or_b32_e32 v160, s2, v128
	v_lshlrev_b32_e32 v128, 1, v164
	v_ashrrev_i32_e32 v129, 31, v128
	v_lshl_add_u64 v[128:129], v[128:129], 2, s[0:1]
	v_readlane_b32 s12, v255, 1
	s_waitcnt vmcnt(8)
	s_barrier
	v_ashrrev_i32_e32 v161, 31, v160
	global_load_dwordx2 v[184:185], v[128:129], off
	v_lshlrev_b64 v[128:129], 12, v[164:165]
	v_readlane_b32 s13, v255, 2
	v_lshlrev_b64 v[166:167], 2, v[160:161]
	v_readlane_b32 s16, v255, 5
	v_lshl_add_u64 v[128:129], s[12:13], 0, v[128:129]
	v_lshl_add_u64 v[128:129], v[128:129], 0, v[166:167]
	global_load_dwordx4 v[168:171], v[128:129], off
	global_load_dwordx4 v[172:175], v[128:129], off offset:16
	global_load_dwordx4 v[176:179], v[128:129], off offset:512
	global_load_dwordx4 v[180:183], v[128:129], off offset:528
	v_readlane_b32 s17, v255, 6
	v_readlane_b32 s18, v255, 7
	v_readlane_b32 s19, v255, 8
	v_lshl_add_u64 v[132:133], s[16:17], 0, v[166:167]
	v_and_b32_e32 v199, 63, v162
	v_lshl_add_u64 v[144:145], s[18:19], 0, v[166:167]
	global_load_dwordx4 v[136:139], v[144:145], off
	global_load_dwordx4 v[156:159], v[132:133], off
	global_load_dwordx4 v[140:143], v[132:133], off offset:16
	global_load_dwordx4 v[152:155], v[144:145], off offset:16
	global_load_dwordx4 v[128:131], v[144:145], off offset:512
	global_load_dwordx4 v[148:151], v[132:133], off offset:512
	s_nop 0
	global_load_dwordx4 v[132:135], v[132:133], off offset:528
	s_nop 0
	global_load_dwordx4 v[144:147], v[144:145], off offset:528
	s_mov_b32 s2, 0x3f9837f0
	v_lshlrev_b32_e32 v186, 2, v199
	v_xor_b32_e32 v200, 64, v186
	v_xor_b32_e32 v203, 0x80, v186
	v_cmp_gt_u32_e32 vcc, 16, v199
	v_readlane_b32 s14, v255, 3
	v_readlane_b32 s15, v255, 4
	v_readlane_b32 s20, v255, 9
	v_readlane_b32 s21, v255, 10
	v_readlane_b32 s22, v255, 11
	v_readlane_b32 s23, v255, 12
	v_readlane_b32 s24, v255, 13
	v_readlane_b32 s25, v255, 14
	v_readlane_b32 s26, v255, 15
	v_readlane_b32 s27, v255, 16
	s_waitcnt vmcnt(0)
	v_sub_f32_e32 v163, v169, v184
	v_sub_f32_e32 v162, v168, v184
	v_sub_f32_e32 v169, v171, v184
	v_sub_f32_e32 v168, v170, v184
	v_sub_f32_e32 v171, v173, v184
	v_sub_f32_e32 v170, v172, v184
	v_sub_f32_e32 v173, v175, v184
	v_sub_f32_e32 v172, v174, v184
	v_pk_mul_f32 v[162:163], v[184:185], v[162:163] op_sel:[1,0]
	v_pk_mul_f32 v[170:171], v[184:185], v[170:171] op_sel:[1,0]
	v_pk_mul_f32 v[168:169], v[184:185], v[168:169] op_sel:[1,0]
	v_pk_mul_f32 v[172:173], v[184:185], v[172:173] op_sel:[1,0]
	v_pk_fma_f32 v[162:163], v[156:157], v[162:163], v[136:137]
	v_pk_fma_f32 v[170:171], v[140:141], v[170:171], v[152:153]
	v_sub_f32_e32 v175, v177, v184
	v_sub_f32_e32 v174, v176, v184
	v_pk_fma_f32 v[168:169], v[158:159], v[168:169], v[138:139]
	v_pk_fma_f32 v[172:173], v[142:143], v[172:173], v[154:155]
	v_pk_fma_f32 v[124:125], v[162:163], s[2:3], v[124:125] op_sel_hi:[1,0,1]
	v_pk_fma_f32 v[120:121], v[170:171], s[2:3], v[120:121] op_sel_hi:[1,0,1]
	v_sub_f32_e32 v177, v179, v184
	v_sub_f32_e32 v176, v178, v184
	v_sub_f32_e32 v179, v181, v184
	v_sub_f32_e32 v178, v180, v184
	v_pk_mul_f32 v[174:175], v[184:185], v[174:175] op_sel:[1,0]
	v_pk_fma_f32 v[126:127], v[168:169], s[2:3], v[126:127] op_sel_hi:[1,0,1]
	v_pk_fma_f32 v[122:123], v[172:173], s[2:3], v[122:123] op_sel_hi:[1,0,1]
	v_pk_add_f32 v[168:169], v[124:125], v[120:121]
	v_pk_mul_f32 v[170:171], v[120:121], v[120:121]
	v_pk_mul_f32 v[176:177], v[184:185], v[176:177] op_sel:[1,0]
	v_pk_mul_f32 v[178:179], v[184:185], v[178:179] op_sel:[1,0]
	v_pk_fma_f32 v[174:175], v[148:149], v[174:175], v[128:129]
	v_pk_mul_f32 v[172:173], v[122:123], v[122:123]
	v_add_f32_e32 v168, 0, v168
	v_pk_fma_f32 v[170:171], v[124:125], v[124:125], v[170:171]
	v_pk_fma_f32 v[176:177], v[150:151], v[176:177], v[130:131]
	v_pk_fma_f32 v[178:179], v[132:133], v[178:179], v[144:145]
	v_pk_fma_f32 v[116:117], v[174:175], s[2:3], v[116:117] op_sel_hi:[1,0,1]
	v_pk_add_f32 v[162:163], v[126:127], v[122:123]
	v_pk_fma_f32 v[172:173], v[126:127], v[126:127], v[172:173]
	v_add_f32_e32 v168, v169, v168
	v_add_f32_e32 v169, v170, v171
	v_sub_f32_e32 v181, v183, v184
	v_sub_f32_e32 v180, v182, v184
	v_pk_fma_f32 v[118:119], v[176:177], s[2:3], v[118:119] op_sel_hi:[1,0,1]
	v_pk_fma_f32 v[112:113], v[178:179], s[2:3], v[112:113] op_sel_hi:[1,0,1]
	v_pk_mul_f32 v[176:177], v[116:117], v[116:117]
	v_add_f32_e32 v162, v162, v168
	v_add_f32_e32 v168, v172, v169
	v_pk_mul_f32 v[180:181], v[184:185], v[180:181] op_sel:[1,0]
	v_pk_add_f32 v[174:175], v[116:117], v[112:113]
	v_pk_fma_f32 v[176:177], v[112:113], v[112:113], v[176:177]
	v_add_f32_e32 v162, v163, v162
	v_add_f32_e32 v163, v173, v168
	v_pk_fma_f32 v[180:181], v[134:135], v[180:181], v[146:147]
	v_add_f32_e32 v168, v174, v162
	v_add_f32_e32 v162, v176, v163
	v_pk_fma_f32 v[114:115], v[180:181], s[2:3], v[114:115] op_sel_hi:[1,0,1]
	v_pk_add_f32 v[162:163], v[176:177], v[162:163] op_sel_hi:[1,0]
	v_mov_b32_e32 v170, v118
	v_mov_b32_e32 v171, v114
	v_mul_f32_e32 v162, v118, v118
	v_pk_fma_f32 v[170:171], v[170:171], v[170:171], v[162:163] op_sel_hi:[1,1,0]
	v_mov_b32_e32 v162, v115
	v_mov_b32_e32 v170, v119
	v_pk_add_f32 v[162:163], v[170:171], v[162:163]
	v_pk_add_f32 v[170:171], v[118:119], v[114:115]
	v_pk_mul_f32 v[172:173], v[118:119], v[118:119]
	v_add_f32_e32 v168, v175, v168
	v_mul_f32_e32 v169, v115, v115
	v_mov_b32_e32 v171, v173
	v_pk_add_f32 v[168:169], v[170:171], v[168:169]
	s_lshl_b32 s3, s85, 3
	v_pk_add_f32 v[162:163], v[168:169], v[162:163]
	ds_bpermute_b32 v168, v200, v162
	ds_bpermute_b32 v169, v200, v163
	s_add_i32 s7, s3, 0
	s_waitcnt lgkmcnt(0)
	v_pk_add_f32 v[162:163], v[162:163], v[168:169]
	ds_bpermute_b32 v168, v203, v162
	ds_bpermute_b32 v169, v203, v163
	s_and_saveexec_b64 s[10:11], vcc
	s_cbranch_execz .LBB0_724
	v_lshl_add_u32 v170, v196, 5, s7
	s_waitcnt lgkmcnt(0)
	v_pk_add_f32 v[162:163], v[162:163], v[168:169]
	ds_write_b64 v170, v[162:163]

; DI float bflo(unsigned w) { return __uint_as_float(w << 16); }
; DI float bfhi(unsigned w) { return __uint_as_float(w & 0xffff0000u); }
; DI float shx(float v, int mask, int lane) { return __int_as_float(__builtin_amdgcn_ds_bpermute((lane ^ mask) << 2, __float_as_int(v))); }
; #define PG8_WAIT_V(n) asm volatile("s_waitcnt vmcnt(" #n ")" ::: "memory")
; #define PG8_BAR __builtin_amdgcn_s_barrier()
; template <class Epi, class Sched, bool ALIGN_EPI = false, bool SP2 = false>
; __device__ __forceinline__ void gemm_phase(PG8_LAS unsigned char* lds, const Gemm g, const Sched& S, const Epi& E, const int wid_s) {
;     ...
;     PG8_WAIT_V(0);
;     if constexpr (!ALIGN_EPI) { if (wr == 0) PG8_BAR; }
;     PG8_BAR;
;     DI void fused(pg8::f32x4 (&acc)[2][2][4][2], const pg8::Unit& u, int wr, int wc, int fr, int fq, pg8::PG8_LAS_T ldsp, int wid, int lane) const {
;     ...
;                     if (MODE == 0) {
;                         const f32x4 x0 = *(const f32x4*)(x + idx), x1 = *(const f32x4*)(x + idx + 4);
;                         v0 = ((x0 - mu) * rs * gi[bj][0] + bi[bj][0]) * ALPHA + acc[ai][bj][m][0];
;                         v1 = ((x1 - mu) * rs * gi[bj][1] + bi[bj][1]) * ALPHA + acc[ai][bj][m][1];
;                     } else {
;                         const u32x4 w = *(const u32x4*)(pg + idx);
;                         const u32x4 hw = *(const u32x4*)(h1 + idx);
;                         v0 = (f32x4){bflo(hw.x), bfhi(hw.x), bflo(hw.y), bfhi(hw.y)} * ALPHA + acc[ai][bj][m][0];
;                         v1 = (f32x4){bflo(hw.z), bfhi(hw.z), bflo(hw.w), bfhi(hw.w)} * ALPHA + acc[ai][bj][m][1];
;                         v0[0] += bflo(w.x); v0[1] += bfhi(w.x); v0[2] += bflo(w.y); v0[3] += bfhi(w.y);
;                         v1[0] += bflo(w.z); v1[1] += bfhi(w.z); v1[2] += bflo(w.w); v1[3] += bfhi(w.w);
;                     }
;                     acc[ai][bj][m][0] = v0; acc[ai][bj][m][1] = v1;
; #pragma unroll
;                     for (int e = 0; e < 4; ++e) { sm += v0[e] + v1[e]; sq += v0[e] * v0[e] + v1[e] * v1[e]; }
;                 }
;                 sm += shx(sm, 16, lane); sm += shx(sm, 32, lane);
;                 sq += shx(sq, 16, lane); sq += shx(sq, 32, lane);
;                 if (fq == 0) { P[(rt * 4 + wc) * 2] = sm; P[(rt * 4 + wc) * 2 + 1] = sq; }
.LBB0_952:
	v_lshrrev_b32_e32 v128, 1, v148
	v_and_b32_e32 v128, 24, v128
	s_lshl_b32 s4, s8, 8
	v_lshl_or_b32 v128, s10, 8, v128
	v_readlane_b32 s0, v255, 35
	s_waitcnt vmcnt(8)
	s_barrier
	v_and_b32_e32 v197, 63, v148
	v_or_b32_e32 v132, s0, v128
	v_add_u32_e32 v128, s4, v196
	v_ashrrev_i32_e32 v129, 31, v128
	v_lshlrev_b64 v[128:129], 10, v[128:129]
	v_ashrrev_i32_e32 v133, 31, v132
	v_lshl_add_u64 v[130:131], v[128:129], 0, v[132:133]
	v_or_b32_e32 v144, 0x80, v132
	v_lshlrev_b64 v[138:139], 1, v[130:131]
	v_ashrrev_i32_e32 v145, 31, v144
	v_lshl_add_u64 v[134:135], s[50:51], 0, v[138:139]
	v_lshl_add_u64 v[128:129], v[128:129], 0, v[144:145]
	global_load_dwordx4 v[134:137], v[134:135], off
	v_lshl_add_u64 v[138:139], s[6:7], 0, v[138:139]
	v_lshlrev_b64 v[128:129], 1, v[128:129]
	global_load_dwordx4 v[138:141], v[138:139], off
	v_lshl_add_u64 v[142:143], s[50:51], 0, v[128:129]
	global_load_dwordx4 v[150:153], v[142:143], off
	v_lshl_add_u64 v[128:129], s[6:7], 0, v[128:129]
	global_load_dwordx4 v[154:157], v[128:129], off
	s_mov_b32 s0, 0x3f9837f0
	v_lshlrev_b32_e32 v160, 2, v197
	v_xor_b32_e32 v198, 64, v160
	v_cmp_gt_u32_e32 vcc, 16, v197
	s_waitcnt vmcnt(0)
	v_lshlrev_b32_e32 v128, 16, v134
	v_and_b32_e32 v129, 0xffff0000, v134
	v_lshlrev_b32_e32 v134, 16, v135
	v_and_b32_e32 v135, 0xffff0000, v135
	v_lshlrev_b32_e32 v142, 16, v136
	v_and_b32_e32 v143, 0xffff0000, v136
	v_lshlrev_b32_e32 v136, 16, v137
	v_and_b32_e32 v137, 0xffff0000, v137
	v_lshlrev_b32_e32 v146, 16, v139
	v_and_b32_e32 v147, 0xffff0000, v139
	v_lshlrev_b32_e32 v159, 16, v141
	v_and_b32_e32 v161, 0xffff0000, v141
	v_and_b32_e32 v141, 0xffff0000, v138
	v_pk_fma_f32 v[128:129], v[128:129], s[0:1], v[124:125] op_sel_hi:[1,0,1]
	v_pk_fma_f32 v[124:125], v[134:135], s[0:1], v[126:127] op_sel_hi:[1,0,1]
	v_pk_fma_f32 v[122:123], v[136:137], s[0:1], v[122:123] op_sel_hi:[1,0,1]
	v_pk_fma_f32 v[134:135], v[142:143], s[0:1], v[120:121] op_sel_hi:[1,0,1]
	v_lshlrev_b32_e32 v148, 16, v140
	v_and_b32_e32 v158, 0xffff0000, v140
	v_lshlrev_b32_e32 v140, 16, v138
	v_mov_b32_e32 v149, v141
	v_lshlrev_b32_e32 v126, 16, v150
	v_and_b32_e32 v127, 0xffff0000, v150
	v_lshlrev_b32_e32 v136, 16, v151
	v_and_b32_e32 v137, 0xffff0000, v151
	v_lshlrev_b32_e32 v142, 16, v153
	v_and_b32_e32 v143, 0xffff0000, v153
	v_pk_add_f32 v[120:121], v[124:125], v[146:147]
	v_pk_mov_b32 v[146:147], v[134:135], v[122:123] op_sel:[1,0]
	v_mov_b32_e32 v135, v129
	v_lshlrev_b32_e32 v138, 16, v152
	v_and_b32_e32 v139, 0xffff0000, v152
	v_lshlrev_b32_e32 v150, 16, v154
	v_and_b32_e32 v151, 0xffff0000, v154
	v_lshlrev_b32_e32 v152, 16, v155
	v_and_b32_e32 v153, 0xffff0000, v155
	v_lshlrev_b32_e32 v154, 16, v156
	v_and_b32_e32 v155, 0xffff0000, v156
	v_lshlrev_b32_e32 v156, 16, v157
	v_and_b32_e32 v157, 0xffff0000, v157
	v_add_f32_e32 v124, v123, v161
	v_pk_add_f32 v[122:123], v[128:129], v[140:141]
	v_pk_fma_f32 v[118:119], v[136:137], s[0:1], v[118:119] op_sel_hi:[1,0,1]
	v_pk_fma_f32 v[116:117], v[126:127], s[0:1], v[116:117] op_sel_hi:[1,0,1]
	v_pk_fma_f32 v[136:137], v[142:143], s[0:1], v[114:115] op_sel_hi:[1,0,1]
	v_pk_add_f32 v[128:129], v[134:135], v[148:149]
	v_pk_fma_f32 v[112:113], v[138:139], s[0:1], v[112:113] op_sel_hi:[1,0,1]
	v_pk_add_f32 v[126:127], v[146:147], v[158:159]
	v_pk_mul_f32 v[134:135], v[122:123], v[122:123]
	v_pk_add_f32 v[114:115], v[116:117], v[150:151]
	v_pk_add_f32 v[116:117], v[118:119], v[152:153]
	v_pk_add_f32 v[118:119], v[136:137], v[156:157]
	v_pk_mul_f32 v[136:137], v[128:129], v[128:129]
	v_pk_add_f32 v[142:143], v[122:123], v[128:129]
	v_pk_mul_f32 v[138:139], v[122:123], v[128:129]
	v_pk_mul_f32 v[146:147], v[126:127], v[126:127]
	v_pk_mov_b32 v[134:135], v[122:123], v[134:135] op_sel:[1,0]
	v_mov_b32_e32 v143, v139
	v_mov_b32_e32 v138, v126
	v_mov_b32_e32 v139, v136
	v_pk_add_f32 v[134:135], v[134:135], v[138:139]
	v_mov_b32_e32 v138, 0
	v_mov_b32_e32 v139, v146
	v_pk_mul_f32 v[140:141], v[120:121], v[120:121]
	v_pk_add_f32 v[136:137], v[142:143], v[138:139]
	v_mov_b32_e32 v146, v127
	v_pk_add_f32 v[134:135], v[134:135], v[136:137]
	v_mov_b32_e32 v136, v120
	v_mov_b32_e32 v137, v140
	v_mul_f32_e32 v125, v124, v124
	v_pk_add_f32 v[112:113], v[112:113], v[154:155]
	v_pk_add_f32 v[136:137], v[136:137], v[146:147]
	v_mov_b32_e32 v140, v121
	v_pk_mul_f32 v[148:149], v[114:115], v[114:115]
	v_pk_mul_f32 v[150:151], v[112:113], v[112:113]
	v_pk_add_f32 v[134:135], v[136:137], v[134:135]
	v_pk_add_f32 v[136:137], v[140:141], v[124:125]
	v_mov_b32_e32 v140, v112
	v_pk_add_f32 v[134:135], v[136:137], v[134:135]
	v_mov_b32_e32 v136, v114
	v_mov_b32_e32 v137, v148
	v_mov_b32_e32 v141, v150
	v_pk_add_f32 v[136:137], v[136:137], v[140:141]
	v_mov_b32_e32 v148, v115
	v_mov_b32_e32 v150, v113
	v_pk_mul_f32 v[152:153], v[116:117], v[116:117]
	v_pk_mul_f32 v[154:155], v[118:119], v[118:119]
	v_pk_add_f32 v[134:135], v[136:137], v[134:135]
	v_pk_add_f32 v[136:137], v[148:149], v[150:151]
	v_mov_b32_e32 v140, v118
	v_pk_add_f32 v[134:135], v[136:137], v[134:135]
	v_mov_b32_e32 v136, v116
	v_mov_b32_e32 v137, v152
	v_mov_b32_e32 v141, v154
	v_pk_add_f32 v[136:137], v[136:137], v[140:141]
	v_mov_b32_e32 v152, v117
	v_mov_b32_e32 v154, v119
	v_pk_add_f32 v[134:135], v[136:137], v[134:135]
	v_pk_add_f32 v[136:137], v[152:153], v[154:155]
	v_xor_b32_e32 v129, 0x80, v160
	v_pk_add_f32 v[134:135], v[136:137], v[134:135]
	ds_bpermute_b32 v136, v198, v134
	ds_bpermute_b32 v137, v198, v135
	s_lshl_b32 s1, s85, 3
	s_add_i32 s5, s1, 0
	s_waitcnt lgkmcnt(0)
	v_pk_add_f32 v[134:135], v[134:135], v[136:137]
	ds_bpermute_b32 v136, v129, v134
	ds_bpermute_b32 v137, v129, v135
	s_and_saveexec_b64 s[2:3], vcc
	s_cbranch_execz .LBB0_954
	v_lshl_add_u32 v125, v196, 5, s5
	s_waitcnt lgkmcnt(0)
	v_pk_add_f32 v[134:135], v[134:135], v[136:137]
	ds_write_b64 v125, v[134:135]
